# v55 + top-k bisection counted with wave-level compares + scalar popcounts (no ds_bpermute reduction chain): the P8 sample top-k wave, now alone on its SIMD, is latency-bound
# speedup vs baseline: 1.0097x; 1.0005x over previous
; #define LDS_WAIT() asm volatile("s_waitcnt lgkmcnt(0)" ::: "memory")
; template <int NPL>
; DI void topk_row2(const float* sc, int n, int* idx_out, LAS unsigned* cbuf  , int lane_) {
;     ...
;     const int ncand = __builtin_amdgcn_readfirstlane(base);
;     if (ncand > TK_CAP) { topk_row<NPL>(sc, n, idx_out, lane_); return; }
;     LDS_WAIT(); asm volatile("" ::: "memory");
;     unsigned ck[TK_CPL], ci[TK_CPL];
; #pragma unroll
;     for (int c = 0; c < TK_CPL; ++c) { const int q = lane2 + 64 * c; const bool v = q < ncand; ck[c] = v ? cbuf[q] : 0u; ci[c] = v ? cbuf[TK_CAP + q] : 0u; }
;     unsigned Tk = 0u;
; #pragma unroll 1
.LBB0_1136:
	s_lshl_b32 s4, s3, 8
	s_ashr_i32 s5, s4, 31
	s_lshl_b64 s[4:5], s[4:5], 2
	s_add_u32 s14, s38, s4
	s_addc_u32 s15, s39, s5
	s_cmpk_lt_i32 s6, 0x401
	s_mov_b64 s[4:5], -1
	s_cbranch_scc0 .LBB0_1236
	s_waitcnt lgkmcnt(0)
	v_cmp_gt_i32_e32 vcc, s6, v5
	v_mov_b32_e32 v32, 0
	v_lshl_add_u32 v50, v5, 2, s40
	v_mov_b32_e32 v34, 0
	v_mov_b32_e32 v35, 0
	s_and_saveexec_b64 s[4:5], vcc
	ds_read2st64_b32 v[34:35], v50 offset1:16
	s_or_b64 exec, exec, s[4:5]
	v_add_u32_e32 v4, 64, v5
	v_cmp_gt_i32_e32 vcc, s6, v4
	v_mov_b32_e32 v33, 0
	s_and_saveexec_b64 s[4:5], vcc
	ds_read2st64_b32 v[32:33], v50 offset0:1 offset1:17
	s_or_b64 exec, exec, s[4:5]
	v_add_u32_e32 v4, 0x80, v5
	v_cmp_gt_i32_e32 vcc, s6, v4
	v_mov_b32_e32 v28, 0
	v_mov_b32_e32 v30, 0
	v_mov_b32_e32 v31, 0
	s_and_saveexec_b64 s[4:5], vcc
	ds_read2st64_b32 v[30:31], v50 offset0:2 offset1:18
	s_or_b64 exec, exec, s[4:5]
	v_add_u32_e32 v4, 0xc0, v5
	v_cmp_gt_i32_e32 vcc, s6, v4
	v_mov_b32_e32 v29, 0
	s_and_saveexec_b64 s[4:5], vcc
	ds_read2st64_b32 v[28:29], v50 offset0:3 offset1:19
	s_or_b64 exec, exec, s[4:5]
	v_add_u32_e32 v4, 0x100, v5
	v_cmp_gt_i32_e32 vcc, s6, v4
	v_mov_b32_e32 v24, 0
	v_mov_b32_e32 v26, 0
	v_mov_b32_e32 v27, 0
	s_and_saveexec_b64 s[4:5], vcc
	ds_read2st64_b32 v[26:27], v50 offset0:4 offset1:20
	s_or_b64 exec, exec, s[4:5]
	v_add_u32_e32 v4, 0x140, v5
	v_cmp_gt_i32_e32 vcc, s6, v4
	v_mov_b32_e32 v25, 0
	s_and_saveexec_b64 s[4:5], vcc
	ds_read2st64_b32 v[24:25], v50 offset0:5 offset1:21
	s_or_b64 exec, exec, s[4:5]
	v_add_u32_e32 v4, 0x180, v5
	v_cmp_gt_i32_e32 vcc, s6, v4
	v_mov_b32_e32 v20, 0
	v_mov_b32_e32 v22, 0
	v_mov_b32_e32 v23, 0
	s_and_saveexec_b64 s[4:5], vcc
	ds_read2st64_b32 v[22:23], v50 offset0:6 offset1:22
	s_or_b64 exec, exec, s[4:5]
	v_add_u32_e32 v4, 0x1c0, v5
	v_cmp_gt_i32_e32 vcc, s6, v4
	v_mov_b32_e32 v21, 0
	s_and_saveexec_b64 s[4:5], vcc
	ds_read2st64_b32 v[20:21], v50 offset0:7 offset1:23
	s_or_b64 exec, exec, s[4:5]
	v_add_u32_e32 v4, 0x200, v5
	v_cmp_gt_i32_e32 vcc, s6, v4
	v_mov_b32_e32 v16, 0
	v_mov_b32_e32 v18, 0
	v_mov_b32_e32 v19, 0
	s_and_saveexec_b64 s[4:5], vcc
	ds_read2st64_b32 v[18:19], v50 offset0:8 offset1:24
	s_or_b64 exec, exec, s[4:5]
	v_add_u32_e32 v4, 0x240, v5
	v_cmp_gt_i32_e32 vcc, s6, v4
	v_mov_b32_e32 v17, 0
	s_and_saveexec_b64 s[4:5], vcc
	ds_read2st64_b32 v[16:17], v50 offset0:9 offset1:25
	s_or_b64 exec, exec, s[4:5]
	v_add_u32_e32 v4, 0x280, v5
	v_cmp_gt_i32_e32 vcc, s6, v4
	v_mov_b32_e32 v12, 0
	v_mov_b32_e32 v14, 0
	v_mov_b32_e32 v15, 0
	s_and_saveexec_b64 s[4:5], vcc
	ds_read2st64_b32 v[14:15], v50 offset0:10 offset1:26
	s_or_b64 exec, exec, s[4:5]
	v_add_u32_e32 v4, 0x2c0, v5
	v_cmp_gt_i32_e32 vcc, s6, v4
	v_mov_b32_e32 v13, 0
	s_and_saveexec_b64 s[4:5], vcc
	ds_read2st64_b32 v[12:13], v50 offset0:11 offset1:27
	s_or_b64 exec, exec, s[4:5]
	v_add_u32_e32 v4, 0x300, v5
	v_cmp_gt_i32_e32 vcc, s6, v4
	v_mov_b32_e32 v8, 0
	v_mov_b32_e32 v10, 0
	v_mov_b32_e32 v11, 0
	s_and_saveexec_b64 s[4:5], vcc
	ds_read2st64_b32 v[10:11], v50 offset0:12 offset1:28
	s_or_b64 exec, exec, s[4:5]
	v_add_u32_e32 v4, 0x340, v5
	v_cmp_gt_i32_e32 vcc, s6, v4
	v_mov_b32_e32 v9, 0
	s_and_saveexec_b64 s[4:5], vcc
	ds_read2st64_b32 v[8:9], v50 offset0:13 offset1:29
	s_or_b64 exec, exec, s[4:5]
	v_add_u32_e32 v4, 0x380, v5
	v_cmp_gt_i32_e32 vcc, s6, v4
	v_mov_b32_e32 v4, 0
	v_mov_b32_e32 v6, 0
	v_mov_b32_e32 v7, 0
	s_and_saveexec_b64 s[4:5], vcc
	ds_read2st64_b32 v[6:7], v50 offset0:14 offset1:30
	s_or_b64 exec, exec, s[4:5]
	v_add_u32_e32 v5, 0x3c0, v5
	v_cmp_gt_i32_e32 vcc, s6, v5
	v_mov_b32_e32 v5, 0
	s_and_saveexec_b64 s[4:5], vcc
	ds_read2st64_b32 v[4:5], v50 offset0:15 offset1:31
	s_or_b64 exec, exec, s[4:5]
	v_mov_b32_e32 v50, 0
	s_mov_b32 s4, 31
	s_mov_b32 s32, 0
; template <int NPL>
; DI void topk_row2(const float* sc, int n, int* idx_out, LAS unsigned* cbuf  , int lane_) {
;     ...
;     unsigned Tk = 0u;
; #pragma unroll 1
;     ...
;         const unsigned cand = __builtin_amdgcn_readfirstlane(Tk | (1u << bit)); int cnt = 0;
; #pragma unroll
;         for (int c = 0; c < TK_CPL; ++c) asm volatile("v_cmp_le_u32 vcc, %2, %1\n\tv_addc_co_u32 %0, vcc, 0, %0, vcc" : "+v"(cnt) : "v"(ck[c]), "s"(cand) : "vcc");
;         cnt = wave_sum_i(cnt);
;         if (cnt >= TOPK) Tk = cand;
;     }
;     int cgt = 0;
;     { const unsigned tks = __builtin_amdgcn_readfirstlane(Tk);
; #pragma unroll
;     for (int c = 0; c < TK_CPL; ++c) asm volatile("v_cmp_lt_u32 vcc, %2, %1\n\tv_addc_co_u32 %0, vcc, 0, %0, vcc" : "+v"(cgt) : "v"(ck[c]), "s"(tks) : "vcc"); }
;     cgt = wave_sum_i(cgt);
;     const int need_eq = TOPK - cgt; int ob = 0, eqb = 0;
; #pragma unroll
;     for (int c = 0; c < TK_CPL; ++c) {
;         const bool gt = ck[c] > Tk, eq = ck[c] == Tk && ck[c] != 0u;
;         const unsigned long long mg = __ballot(gt), me = __ballot(eq);
;         if (gt) idx_out[ob + __builtin_popcountll(mg & below)] = (int)ci[c];
;         const int re = eqb + __builtin_popcountll(me & below);
;         if (eq && re < need_eq) idx_out[cgt + re] = (int)ci[c];
.LBB0_1170:
	s_waitcnt lgkmcnt(0)
	s_lshl_b32 s5, 1, s4
	s_or_b32 s5, s5, s32
	v_cmp_le_u32_e64 vcc, s5, v34
	v_cmp_le_u32_e64 s[6:7], s5, v32
	s_bcnt1_i32_b64 s100, vcc
	s_bcnt1_i32_b64 s101, s[6:7]
	s_add_i32 s100, s100, s101
	v_cmp_le_u32_e64 vcc, s5, v30
	v_cmp_le_u32_e64 s[6:7], s5, v28
	s_bcnt1_i32_b64 s101, vcc
	s_add_i32 s100, s100, s101
	s_bcnt1_i32_b64 s101, s[6:7]
	s_add_i32 s100, s100, s101
	v_cmp_le_u32_e64 vcc, s5, v26
	v_cmp_le_u32_e64 s[6:7], s5, v24
	s_bcnt1_i32_b64 s101, vcc
	s_add_i32 s100, s100, s101
	s_bcnt1_i32_b64 s101, s[6:7]
	s_add_i32 s100, s100, s101
	v_cmp_le_u32_e64 vcc, s5, v22
	v_cmp_le_u32_e64 s[6:7], s5, v20
	s_bcnt1_i32_b64 s101, vcc
	s_add_i32 s100, s100, s101
	s_bcnt1_i32_b64 s101, s[6:7]
	s_add_i32 s100, s100, s101
	v_cmp_le_u32_e64 vcc, s5, v18
	v_cmp_le_u32_e64 s[6:7], s5, v16
	s_bcnt1_i32_b64 s101, vcc
	s_add_i32 s100, s100, s101
	s_bcnt1_i32_b64 s101, s[6:7]
	s_add_i32 s100, s100, s101
	v_cmp_le_u32_e64 vcc, s5, v14
	v_cmp_le_u32_e64 s[6:7], s5, v12
	s_bcnt1_i32_b64 s101, vcc
	s_add_i32 s100, s100, s101
	s_bcnt1_i32_b64 s101, s[6:7]
	s_add_i32 s100, s100, s101
	v_cmp_le_u32_e64 vcc, s5, v10
	v_cmp_le_u32_e64 s[6:7], s5, v8
	s_bcnt1_i32_b64 s101, vcc
	s_add_i32 s100, s100, s101
	s_bcnt1_i32_b64 s101, s[6:7]
	s_add_i32 s100, s100, s101
	v_cmp_le_u32_e64 vcc, s5, v6
	v_cmp_le_u32_e64 s[6:7], s5, v4
	s_bcnt1_i32_b64 s101, vcc
	s_add_i32 s100, s100, s101
	s_bcnt1_i32_b64 s101, s[6:7]
	s_add_i32 s100, s100, s101
	s_cmp_gt_i32 s100, s73
	s_cselect_b32 s32, s5, s32
	s_add_i32 s4, s4, -1
	s_cmp_eq_u32 s4, -1
	s_cbranch_scc0 .LBB0_1170
	v_mov_b32_e32 v50, s32
	v_mov_b32_e32 v51, 0
	v_readfirstlane_b32 s4, v50
	v_cmp_lt_u32 vcc, s4, v34
	v_addc_co_u32 v51, vcc, 0, v51, vcc
	v_cmp_ne_u32_e64 s[6:7], 0, v34
	v_cmp_lt_u32 vcc, s4, v32
	v_addc_co_u32 v51, vcc, 0, v51, vcc
	s_nop 0
	v_cmp_lt_u32 vcc, s4, v30
	v_addc_co_u32 v51, vcc, 0, v51, vcc
	s_nop 0
	v_cmp_lt_u32 vcc, s4, v28
	v_addc_co_u32 v51, vcc, 0, v51, vcc
	s_nop 0
	v_cmp_lt_u32 vcc, s4, v26
	v_addc_co_u32 v51, vcc, 0, v51, vcc
	s_nop 0
	v_cmp_lt_u32 vcc, s4, v24
	v_addc_co_u32 v51, vcc, 0, v51, vcc
	s_nop 0
	v_cmp_lt_u32 vcc, s4, v22
	v_addc_co_u32 v51, vcc, 0, v51, vcc
	s_nop 0
	v_cmp_lt_u32 vcc, s4, v20
	v_addc_co_u32 v51, vcc, 0, v51, vcc
	s_nop 0
	v_cmp_lt_u32 vcc, s4, v18
	v_addc_co_u32 v51, vcc, 0, v51, vcc
	s_nop 0
	v_cmp_lt_u32 vcc, s4, v16
	v_addc_co_u32 v51, vcc, 0, v51, vcc
	s_nop 0
	v_cmp_lt_u32 vcc, s4, v14
	v_addc_co_u32 v51, vcc, 0, v51, vcc
	s_nop 0
	v_cmp_lt_u32 vcc, s4, v12
	v_addc_co_u32 v51, vcc, 0, v51, vcc
	s_nop 0
	v_cmp_lt_u32 vcc, s4, v10
	v_addc_co_u32 v51, vcc, 0, v51, vcc
	s_nop 0
	v_cmp_lt_u32 vcc, s4, v8
	v_addc_co_u32 v51, vcc, 0, v51, vcc
	s_nop 0
	v_cmp_lt_u32 vcc, s4, v6
	v_addc_co_u32 v51, vcc, 0, v51, vcc
	s_nop 0
	v_cmp_lt_u32 vcc, s4, v4
	v_addc_co_u32 v51, vcc, 0, v51, vcc
	ds_bpermute_b32 v52, v45, v51
	v_cmp_eq_u32_e64 s[4:5], v34, v50
	s_and_b64 s[8:9], s[6:7], s[4:5]
	v_cmp_gt_u32_e32 vcc, v34, v50
	v_cndmask_b32_e64 v34, 0, 1, s[8:9]
	s_waitcnt lgkmcnt(0)
	v_add_u32_e32 v51, v52, v51
	ds_bpermute_b32 v52, v46, v51
	v_cmp_ne_u32_e64 s[4:5], 0, v34
	s_waitcnt lgkmcnt(0)
	v_add_u32_e32 v51, v52, v51
	ds_bpermute_b32 v52, v47, v51
	s_waitcnt lgkmcnt(0)
	v_add_u32_e32 v51, v52, v51
	ds_bpermute_b32 v52, v48, v51
	s_waitcnt lgkmcnt(0)
	v_add_u32_e32 v51, v52, v51
	ds_bpermute_b32 v52, v49, v51
	s_waitcnt lgkmcnt(0)
	v_add_u32_e32 v51, v52, v51
	ds_bpermute_b32 v52, v44, v51
	s_and_saveexec_b64 s[6:7], vcc
	s_cbranch_execz .LBB0_1173
	v_and_b32_e32 v53, vcc_lo, v2
	v_and_b32_e32 v34, vcc_hi, v1
	v_bcnt_u32_b32 v53, v53, 0
	v_bcnt_u32_b32 v34, v34, v53
	v_lshlrev_b32_e32 v34, 2, v34
	global_store_dword v34, v35, s[14:15]

; #define LDS_WAIT() asm volatile("s_waitcnt lgkmcnt(0)" ::: "memory")
; template <int NPL>
; DI void topk_row2(const float* sc, int n, int* idx_out, LAS unsigned* cbuf  , int lane_) {
;     ...
;     const int ncand = __builtin_amdgcn_readfirstlane(base);
;     if (ncand > TK_CAP) { topk_row<NPL>(sc, n, idx_out, lane_); return; }
;     LDS_WAIT(); asm volatile("" ::: "memory");
;     unsigned ck[TK_CPL], ci[TK_CPL];
; #pragma unroll
;     for (int c = 0; c < TK_CPL; ++c) { const int q = lane2 + 64 * c; const bool v = q < ncand; ck[c] = v ? cbuf[q] : 0u; ci[c] = v ? cbuf[TK_CAP + q] : 0u; }
;     unsigned Tk = 0u;
; #pragma unroll 1
.LBB0_2122:
	s_cmpk_lt_i32 s6, 0x401
	s_mov_b64 s[14:15], -1
	s_cbranch_scc0 .LBB0_2222
	s_waitcnt lgkmcnt(0)
	v_cmp_gt_i32_e32 vcc, s6, v60
	v_mov_b32_e32 v30, 0
	v_lshl_add_u32 v40, v60, 2, s3
	v_mov_b32_e32 v32, 0
	v_mov_b32_e32 v33, 0
	s_and_saveexec_b64 s[14:15], vcc
	ds_read2st64_b32 v[32:33], v40 offset1:16
	s_or_b64 exec, exec, s[14:15]
	v_add_u32_e32 v2, 64, v60
	v_cmp_gt_i32_e32 vcc, s6, v2
	v_mov_b32_e32 v31, 0
	s_and_saveexec_b64 s[14:15], vcc
	ds_read2st64_b32 v[30:31], v40 offset0:1 offset1:17
	s_or_b64 exec, exec, s[14:15]
	v_add_u32_e32 v2, 0x80, v60
	v_cmp_gt_i32_e32 vcc, s6, v2
	v_mov_b32_e32 v26, 0
	v_mov_b32_e32 v28, 0
	v_mov_b32_e32 v29, 0
	s_and_saveexec_b64 s[14:15], vcc
	ds_read2st64_b32 v[28:29], v40 offset0:2 offset1:18
	s_or_b64 exec, exec, s[14:15]
	v_add_u32_e32 v2, 0xc0, v60
	v_cmp_gt_i32_e32 vcc, s6, v2
	v_mov_b32_e32 v27, 0
	s_and_saveexec_b64 s[14:15], vcc
	ds_read2st64_b32 v[26:27], v40 offset0:3 offset1:19
	s_or_b64 exec, exec, s[14:15]
	v_add_u32_e32 v2, 0x100, v60
	v_cmp_gt_i32_e32 vcc, s6, v2
	v_mov_b32_e32 v22, 0
	v_mov_b32_e32 v24, 0
	v_mov_b32_e32 v25, 0
	s_and_saveexec_b64 s[14:15], vcc
	ds_read2st64_b32 v[24:25], v40 offset0:4 offset1:20
	s_or_b64 exec, exec, s[14:15]
	v_add_u32_e32 v2, 0x140, v60
	v_cmp_gt_i32_e32 vcc, s6, v2
	v_mov_b32_e32 v23, 0
	s_and_saveexec_b64 s[14:15], vcc
	ds_read2st64_b32 v[22:23], v40 offset0:5 offset1:21
	s_or_b64 exec, exec, s[14:15]
	v_add_u32_e32 v2, 0x180, v60
	v_cmp_gt_i32_e32 vcc, s6, v2
	v_mov_b32_e32 v18, 0
	v_mov_b32_e32 v20, 0
	v_mov_b32_e32 v21, 0
	s_and_saveexec_b64 s[14:15], vcc
	ds_read2st64_b32 v[20:21], v40 offset0:6 offset1:22
	s_or_b64 exec, exec, s[14:15]
	v_add_u32_e32 v2, 0x1c0, v60
	v_cmp_gt_i32_e32 vcc, s6, v2
	v_mov_b32_e32 v19, 0
	s_and_saveexec_b64 s[14:15], vcc
	ds_read2st64_b32 v[18:19], v40 offset0:7 offset1:23
	s_or_b64 exec, exec, s[14:15]
	v_add_u32_e32 v2, 0x200, v60
	v_cmp_gt_i32_e32 vcc, s6, v2
	v_mov_b32_e32 v14, 0
	v_mov_b32_e32 v16, 0
	v_mov_b32_e32 v17, 0
	s_and_saveexec_b64 s[14:15], vcc
	ds_read2st64_b32 v[16:17], v40 offset0:8 offset1:24
	s_or_b64 exec, exec, s[14:15]
	v_add_u32_e32 v2, 0x240, v60
	v_cmp_gt_i32_e32 vcc, s6, v2
	v_mov_b32_e32 v15, 0
	s_and_saveexec_b64 s[14:15], vcc
	ds_read2st64_b32 v[14:15], v40 offset0:9 offset1:25
	s_or_b64 exec, exec, s[14:15]
	v_add_u32_e32 v2, 0x280, v60
	v_cmp_gt_i32_e32 vcc, s6, v2
	v_mov_b32_e32 v10, 0
	v_mov_b32_e32 v12, 0
	v_mov_b32_e32 v13, 0
	s_and_saveexec_b64 s[14:15], vcc
	ds_read2st64_b32 v[12:13], v40 offset0:10 offset1:26
	s_or_b64 exec, exec, s[14:15]
	v_add_u32_e32 v2, 0x2c0, v60
	v_cmp_gt_i32_e32 vcc, s6, v2
	v_mov_b32_e32 v11, 0
	s_and_saveexec_b64 s[14:15], vcc
	ds_read2st64_b32 v[10:11], v40 offset0:11 offset1:27
	s_or_b64 exec, exec, s[14:15]
	v_add_u32_e32 v2, 0x300, v60
	v_cmp_gt_i32_e32 vcc, s6, v2
	v_mov_b32_e32 v6, 0
	v_mov_b32_e32 v8, 0
	v_mov_b32_e32 v9, 0
	s_and_saveexec_b64 s[14:15], vcc
	ds_read2st64_b32 v[8:9], v40 offset0:12 offset1:28
	s_or_b64 exec, exec, s[14:15]
	v_add_u32_e32 v2, 0x340, v60
	v_cmp_gt_i32_e32 vcc, s6, v2
	v_mov_b32_e32 v7, 0
	s_and_saveexec_b64 s[14:15], vcc
	ds_read2st64_b32 v[6:7], v40 offset0:13 offset1:29
	s_or_b64 exec, exec, s[14:15]
	v_add_u32_e32 v2, 0x380, v60
	v_cmp_gt_i32_e32 vcc, s6, v2
	v_mov_b32_e32 v2, 0
	v_mov_b32_e32 v4, 0
	v_mov_b32_e32 v5, 0
	s_and_saveexec_b64 s[14:15], vcc
	ds_read2st64_b32 v[4:5], v40 offset0:14 offset1:30
	s_or_b64 exec, exec, s[14:15]
	v_add_u32_e32 v3, 0x3c0, v60
	v_cmp_gt_i32_e32 vcc, s6, v3
	v_mov_b32_e32 v3, 0
	s_and_saveexec_b64 s[14:15], vcc
	ds_read2st64_b32 v[2:3], v40 offset0:15 offset1:31
	s_or_b64 exec, exec, s[14:15]
	v_mov_b32_e32 v40, 0
	s_mov_b32 s6, 31
	s_mov_b32 s32, 0
; template <int NPL>
; DI void topk_row2(const float* sc, int n, int* idx_out, LAS unsigned* cbuf  , int lane_) {
;     ...
;     unsigned Tk = 0u;
; #pragma unroll 1
;     ...
;         const unsigned cand = __builtin_amdgcn_readfirstlane(Tk | (1u << bit)); int cnt = 0;
; #pragma unroll
;         for (int c = 0; c < TK_CPL; ++c) asm volatile("v_cmp_le_u32 vcc, %2, %1\n\tv_addc_co_u32 %0, vcc, 0, %0, vcc" : "+v"(cnt) : "v"(ck[c]), "s"(cand) : "vcc");
;         cnt = wave_sum_i(cnt);
;         if (cnt >= TOPK) Tk = cand;
;     }
;     int cgt = 0;
;     { const unsigned tks = __builtin_amdgcn_readfirstlane(Tk);
; #pragma unroll
;     for (int c = 0; c < TK_CPL; ++c) asm volatile("v_cmp_lt_u32 vcc, %2, %1\n\tv_addc_co_u32 %0, vcc, 0, %0, vcc" : "+v"(cgt) : "v"(ck[c]), "s"(tks) : "vcc"); }
;     cgt = wave_sum_i(cgt);
;     const int need_eq = TOPK - cgt; int ob = 0, eqb = 0;
; #pragma unroll
;     for (int c = 0; c < TK_CPL; ++c) {
;         const bool gt = ck[c] > Tk, eq = ck[c] == Tk && ck[c] != 0u;
;         const unsigned long long mg = __ballot(gt), me = __ballot(eq);
;         if (gt) idx_out[ob + __builtin_popcountll(mg & below)] = (int)ci[c];
;         const int re = eqb + __builtin_popcountll(me & below);
;         if (eq && re < need_eq) idx_out[cgt + re] = (int)ci[c];
.LBB0_2156:
	s_waitcnt lgkmcnt(0)
	s_lshl_b32 s7, 1, s6
	s_or_b32 s7, s7, s32
	v_cmp_le_u32_e64 vcc, s7, v32
	v_cmp_le_u32_e64 s[14:15], s7, v30
	s_bcnt1_i32_b64 s100, vcc
	s_bcnt1_i32_b64 s101, s[14:15]
	s_add_i32 s100, s100, s101
	v_cmp_le_u32_e64 vcc, s7, v28
	v_cmp_le_u32_e64 s[14:15], s7, v26
	s_bcnt1_i32_b64 s101, vcc
	s_add_i32 s100, s100, s101
	s_bcnt1_i32_b64 s101, s[14:15]
	s_add_i32 s100, s100, s101
	v_cmp_le_u32_e64 vcc, s7, v24
	v_cmp_le_u32_e64 s[14:15], s7, v22
	s_bcnt1_i32_b64 s101, vcc
	s_add_i32 s100, s100, s101
	s_bcnt1_i32_b64 s101, s[14:15]
	s_add_i32 s100, s100, s101
	v_cmp_le_u32_e64 vcc, s7, v20
	v_cmp_le_u32_e64 s[14:15], s7, v18
	s_bcnt1_i32_b64 s101, vcc
	s_add_i32 s100, s100, s101
	s_bcnt1_i32_b64 s101, s[14:15]
	s_add_i32 s100, s100, s101
	v_cmp_le_u32_e64 vcc, s7, v16
	v_cmp_le_u32_e64 s[14:15], s7, v14
	s_bcnt1_i32_b64 s101, vcc
	s_add_i32 s100, s100, s101
	s_bcnt1_i32_b64 s101, s[14:15]
	s_add_i32 s100, s100, s101
	v_cmp_le_u32_e64 vcc, s7, v12
	v_cmp_le_u32_e64 s[14:15], s7, v10
	s_bcnt1_i32_b64 s101, vcc
	s_add_i32 s100, s100, s101
	s_bcnt1_i32_b64 s101, s[14:15]
	s_add_i32 s100, s100, s101
	v_cmp_le_u32_e64 vcc, s7, v8
	v_cmp_le_u32_e64 s[14:15], s7, v6
	s_bcnt1_i32_b64 s101, vcc
	s_add_i32 s100, s100, s101
	s_bcnt1_i32_b64 s101, s[14:15]
	s_add_i32 s100, s100, s101
	v_cmp_le_u32_e64 vcc, s7, v4
	v_cmp_le_u32_e64 s[14:15], s7, v2
	s_bcnt1_i32_b64 s101, vcc
	s_add_i32 s100, s100, s101
	s_bcnt1_i32_b64 s101, s[14:15]
	s_add_i32 s100, s100, s101
	s_cmp_gt_i32 s100, s50
	s_cselect_b32 s32, s7, s32
	s_add_i32 s6, s6, -1
	s_cmp_eq_u32 s6, -1
	s_cbranch_scc0 .LBB0_2156
	v_mov_b32_e32 v40, s32
	v_mov_b32_e32 v41, v103
	v_readfirstlane_b32 s6, v40
	v_cmp_lt_u32 vcc, s6, v32
	v_addc_co_u32 v41, vcc, 0, v41, vcc
	v_cmp_eq_u32_e64 s[14:15], v32, v40
	v_cmp_lt_u32 vcc, s6, v30
	v_addc_co_u32 v41, vcc, 0, v41, vcc
	v_cmp_ne_u32_e64 s[16:17], 0, v32
	v_cmp_lt_u32 vcc, s6, v28
	v_addc_co_u32 v41, vcc, 0, v41, vcc
	s_and_b64 s[18:19], s[16:17], s[14:15]
	v_cmp_lt_u32 vcc, s6, v26
	v_addc_co_u32 v41, vcc, 0, v41, vcc
	s_nop 0
	v_cmp_lt_u32 vcc, s6, v24
	v_addc_co_u32 v41, vcc, 0, v41, vcc
	s_nop 0
	v_cmp_lt_u32 vcc, s6, v22
	v_addc_co_u32 v41, vcc, 0, v41, vcc
	s_nop 0
	v_cmp_lt_u32 vcc, s6, v20
	v_addc_co_u32 v41, vcc, 0, v41, vcc
	s_nop 0
	v_cmp_lt_u32 vcc, s6, v18
	v_addc_co_u32 v41, vcc, 0, v41, vcc
	s_nop 0
	v_cmp_lt_u32 vcc, s6, v16
	v_addc_co_u32 v41, vcc, 0, v41, vcc
	s_nop 0
	v_cmp_lt_u32 vcc, s6, v14
	v_addc_co_u32 v41, vcc, 0, v41, vcc
	s_nop 0
	v_cmp_lt_u32 vcc, s6, v12
	v_addc_co_u32 v41, vcc, 0, v41, vcc
	s_nop 0
	v_cmp_lt_u32 vcc, s6, v10
	v_addc_co_u32 v41, vcc, 0, v41, vcc
	s_nop 0
	v_cmp_lt_u32 vcc, s6, v8
	v_addc_co_u32 v41, vcc, 0, v41, vcc
	s_nop 0
	v_cmp_lt_u32 vcc, s6, v6
	v_addc_co_u32 v41, vcc, 0, v41, vcc
	s_nop 0
	v_cmp_lt_u32 vcc, s6, v4
	v_addc_co_u32 v41, vcc, 0, v41, vcc
	s_nop 0
	v_cmp_lt_u32 vcc, s6, v2
	v_addc_co_u32 v41, vcc, 0, v41, vcc
	ds_bpermute_b32 v42, v35, v41
	v_cmp_gt_u32_e32 vcc, v32, v40
	v_cndmask_b32_e64 v32, 0, 1, s[18:19]
	v_cmp_ne_u32_e64 s[14:15], 0, v32
	s_waitcnt lgkmcnt(0)
	v_add_u32_e32 v41, v42, v41
	ds_bpermute_b32 v42, v36, v41
	s_waitcnt lgkmcnt(0)
	v_add_u32_e32 v41, v42, v41
	ds_bpermute_b32 v42, v37, v41
	s_waitcnt lgkmcnt(0)
	v_add_u32_e32 v41, v42, v41
	ds_bpermute_b32 v42, v38, v41
	s_waitcnt lgkmcnt(0)
	v_add_u32_e32 v41, v42, v41
	ds_bpermute_b32 v42, v39, v41
	s_waitcnt lgkmcnt(0)
	v_add_u32_e32 v41, v42, v41
	ds_bpermute_b32 v42, v34, v41
	s_and_saveexec_b64 s[16:17], vcc
	s_cbranch_execz .LBB0_2159
	v_and_b32_e32 v43, vcc_lo, v0
	v_and_b32_e32 v32, vcc_hi, v1
	v_bcnt_u32_b32 v43, v43, 0
	v_bcnt_u32_b32 v32, v32, v43
	v_lshlrev_b32_e32 v32, 2, v32
	global_store_dword v32, v33, s[42:43]

; #define LDS_WAIT() asm volatile("s_waitcnt lgkmcnt(0)" ::: "memory")
; template <int NPL>
; DI void topk_row2(const float* sc, int n, int* idx_out, LAS unsigned* cbuf  , int lane_) {
;     ...
;     const int ncand = __builtin_amdgcn_readfirstlane(base);
;     if (ncand > TK_CAP) { topk_row<NPL>(sc, n, idx_out, lane_); return; }
;     LDS_WAIT(); asm volatile("" ::: "memory");
;     unsigned ck[TK_CPL], ci[TK_CPL];
; #pragma unroll
;     for (int c = 0; c < TK_CPL; ++c) { const int q = lane2 + 64 * c; const bool v = q < ncand; ck[c] = v ? cbuf[q] : 0u; ci[c] = v ? cbuf[TK_CAP + q] : 0u; }
;     unsigned Tk = 0u;
; #pragma unroll 1
.LBB0_3380:
	s_cmpk_lt_i32 s16, 0x401
	s_mov_b64 s[14:15], -1
	s_cbranch_scc0 .LBB0_3480
	s_waitcnt lgkmcnt(0)
	v_cmp_gt_i32_e32 vcc, s16, v44
	v_mov_b32_e32 v30, 0
	v_lshl_add_u32 v40, v44, 2, s3
	v_mov_b32_e32 v32, 0
	v_mov_b32_e32 v33, 0
	s_and_saveexec_b64 s[14:15], vcc
	ds_read2st64_b32 v[32:33], v40 offset1:16
	s_or_b64 exec, exec, s[14:15]
	v_add_u32_e32 v2, 64, v44
	v_cmp_gt_i32_e32 vcc, s16, v2
	v_mov_b32_e32 v31, 0
	s_and_saveexec_b64 s[14:15], vcc
	ds_read2st64_b32 v[30:31], v40 offset0:1 offset1:17
	s_or_b64 exec, exec, s[14:15]
	v_add_u32_e32 v2, 0x80, v44
	v_cmp_gt_i32_e32 vcc, s16, v2
	v_mov_b32_e32 v26, 0
	v_mov_b32_e32 v28, 0
	v_mov_b32_e32 v29, 0
	s_and_saveexec_b64 s[14:15], vcc
	ds_read2st64_b32 v[28:29], v40 offset0:2 offset1:18
	s_or_b64 exec, exec, s[14:15]
	v_add_u32_e32 v2, 0xc0, v44
	v_cmp_gt_i32_e32 vcc, s16, v2
	v_mov_b32_e32 v27, 0
	s_and_saveexec_b64 s[14:15], vcc
	ds_read2st64_b32 v[26:27], v40 offset0:3 offset1:19
	s_or_b64 exec, exec, s[14:15]
	v_add_u32_e32 v2, 0x100, v44
	v_cmp_gt_i32_e32 vcc, s16, v2
	v_mov_b32_e32 v22, 0
	v_mov_b32_e32 v24, 0
	v_mov_b32_e32 v25, 0
	s_and_saveexec_b64 s[14:15], vcc
	ds_read2st64_b32 v[24:25], v40 offset0:4 offset1:20
	s_or_b64 exec, exec, s[14:15]
	v_add_u32_e32 v2, 0x140, v44
	v_cmp_gt_i32_e32 vcc, s16, v2
	v_mov_b32_e32 v23, 0
	s_and_saveexec_b64 s[14:15], vcc
	ds_read2st64_b32 v[22:23], v40 offset0:5 offset1:21
	s_or_b64 exec, exec, s[14:15]
	v_add_u32_e32 v2, 0x180, v44
	v_cmp_gt_i32_e32 vcc, s16, v2
	v_mov_b32_e32 v18, 0
	v_mov_b32_e32 v20, 0
	v_mov_b32_e32 v21, 0
	s_and_saveexec_b64 s[14:15], vcc
	ds_read2st64_b32 v[20:21], v40 offset0:6 offset1:22
	s_or_b64 exec, exec, s[14:15]
	v_add_u32_e32 v2, 0x1c0, v44
	v_cmp_gt_i32_e32 vcc, s16, v2
	v_mov_b32_e32 v19, 0
	s_and_saveexec_b64 s[14:15], vcc
	ds_read2st64_b32 v[18:19], v40 offset0:7 offset1:23
	s_or_b64 exec, exec, s[14:15]
	v_add_u32_e32 v2, 0x200, v44
	v_cmp_gt_i32_e32 vcc, s16, v2
	v_mov_b32_e32 v14, 0
	v_mov_b32_e32 v16, 0
	v_mov_b32_e32 v17, 0
	s_and_saveexec_b64 s[14:15], vcc
	ds_read2st64_b32 v[16:17], v40 offset0:8 offset1:24
	s_or_b64 exec, exec, s[14:15]
	v_add_u32_e32 v2, 0x240, v44
	v_cmp_gt_i32_e32 vcc, s16, v2
	v_mov_b32_e32 v15, 0
	s_and_saveexec_b64 s[14:15], vcc
	ds_read2st64_b32 v[14:15], v40 offset0:9 offset1:25
	s_or_b64 exec, exec, s[14:15]
	v_add_u32_e32 v2, 0x280, v44
	v_cmp_gt_i32_e32 vcc, s16, v2
	v_mov_b32_e32 v10, 0
	v_mov_b32_e32 v12, 0
	v_mov_b32_e32 v13, 0
	s_and_saveexec_b64 s[14:15], vcc
	ds_read2st64_b32 v[12:13], v40 offset0:10 offset1:26
	s_or_b64 exec, exec, s[14:15]
	v_add_u32_e32 v2, 0x2c0, v44
	v_cmp_gt_i32_e32 vcc, s16, v2
	v_mov_b32_e32 v11, 0
	s_and_saveexec_b64 s[14:15], vcc
	ds_read2st64_b32 v[10:11], v40 offset0:11 offset1:27
	s_or_b64 exec, exec, s[14:15]
	v_add_u32_e32 v2, 0x300, v44
	v_cmp_gt_i32_e32 vcc, s16, v2
	v_mov_b32_e32 v6, 0
	v_mov_b32_e32 v8, 0
	v_mov_b32_e32 v9, 0
	s_and_saveexec_b64 s[14:15], vcc
	ds_read2st64_b32 v[8:9], v40 offset0:12 offset1:28
	s_or_b64 exec, exec, s[14:15]
	v_add_u32_e32 v2, 0x340, v44
	v_cmp_gt_i32_e32 vcc, s16, v2
	v_mov_b32_e32 v7, 0
	s_and_saveexec_b64 s[14:15], vcc
	ds_read2st64_b32 v[6:7], v40 offset0:13 offset1:29
	s_or_b64 exec, exec, s[14:15]
	v_add_u32_e32 v2, 0x380, v44
	v_cmp_gt_i32_e32 vcc, s16, v2
	v_mov_b32_e32 v2, 0
	v_mov_b32_e32 v4, 0
	v_mov_b32_e32 v5, 0
	s_and_saveexec_b64 s[14:15], vcc
	ds_read2st64_b32 v[4:5], v40 offset0:14 offset1:30
	s_or_b64 exec, exec, s[14:15]
	v_add_u32_e32 v3, 0x3c0, v44
	v_cmp_gt_i32_e32 vcc, s16, v3
	v_mov_b32_e32 v3, 0
	s_and_saveexec_b64 s[14:15], vcc
	ds_read2st64_b32 v[2:3], v40 offset0:15 offset1:31
	s_or_b64 exec, exec, s[14:15]
	v_mov_b32_e32 v40, 0
	s_mov_b32 s14, 31
	s_mov_b32 s32, 0
; template <int NPL>
; DI void topk_row2(const float* sc, int n, int* idx_out, LAS unsigned* cbuf  , int lane_) {
;     ...
;     unsigned Tk = 0u;
; #pragma unroll 1
;     ...
;         const unsigned cand = __builtin_amdgcn_readfirstlane(Tk | (1u << bit)); int cnt = 0;
; #pragma unroll
;         for (int c = 0; c < TK_CPL; ++c) asm volatile("v_cmp_le_u32 vcc, %2, %1\n\tv_addc_co_u32 %0, vcc, 0, %0, vcc" : "+v"(cnt) : "v"(ck[c]), "s"(cand) : "vcc");
;         cnt = wave_sum_i(cnt);
;         if (cnt >= TOPK) Tk = cand;
;     }
;     int cgt = 0;
;     { const unsigned tks = __builtin_amdgcn_readfirstlane(Tk);
; #pragma unroll
;     for (int c = 0; c < TK_CPL; ++c) asm volatile("v_cmp_lt_u32 vcc, %2, %1\n\tv_addc_co_u32 %0, vcc, 0, %0, vcc" : "+v"(cgt) : "v"(ck[c]), "s"(tks) : "vcc"); }
;     cgt = wave_sum_i(cgt);
;     const int need_eq = TOPK - cgt; int ob = 0, eqb = 0;
; #pragma unroll
;     for (int c = 0; c < TK_CPL; ++c) {
;         const bool gt = ck[c] > Tk, eq = ck[c] == Tk && ck[c] != 0u;
;         const unsigned long long mg = __ballot(gt), me = __ballot(eq);
;         if (gt) idx_out[ob + __builtin_popcountll(mg & below)] = (int)ci[c];
;         const int re = eqb + __builtin_popcountll(me & below);
;         if (eq && re < need_eq) idx_out[cgt + re] = (int)ci[c];
.LBB0_3414:
	s_waitcnt lgkmcnt(0)
	s_lshl_b32 s15, 1, s14
	s_or_b32 s15, s15, s32
	v_cmp_le_u32_e64 vcc, s15, v32
	v_cmp_le_u32_e64 s[16:17], s15, v30
	s_bcnt1_i32_b64 s100, vcc
	s_bcnt1_i32_b64 s101, s[16:17]
	s_add_i32 s100, s100, s101
	v_cmp_le_u32_e64 vcc, s15, v28
	v_cmp_le_u32_e64 s[16:17], s15, v26
	s_bcnt1_i32_b64 s101, vcc
	s_add_i32 s100, s100, s101
	s_bcnt1_i32_b64 s101, s[16:17]
	s_add_i32 s100, s100, s101
	v_cmp_le_u32_e64 vcc, s15, v24
	v_cmp_le_u32_e64 s[16:17], s15, v22
	s_bcnt1_i32_b64 s101, vcc
	s_add_i32 s100, s100, s101
	s_bcnt1_i32_b64 s101, s[16:17]
	s_add_i32 s100, s100, s101
	v_cmp_le_u32_e64 vcc, s15, v20
	v_cmp_le_u32_e64 s[16:17], s15, v18
	s_bcnt1_i32_b64 s101, vcc
	s_add_i32 s100, s100, s101
	s_bcnt1_i32_b64 s101, s[16:17]
	s_add_i32 s100, s100, s101
	v_cmp_le_u32_e64 vcc, s15, v16
	v_cmp_le_u32_e64 s[16:17], s15, v14
	s_bcnt1_i32_b64 s101, vcc
	s_add_i32 s100, s100, s101
	s_bcnt1_i32_b64 s101, s[16:17]
	s_add_i32 s100, s100, s101
	v_cmp_le_u32_e64 vcc, s15, v12
	v_cmp_le_u32_e64 s[16:17], s15, v10
	s_bcnt1_i32_b64 s101, vcc
	s_add_i32 s100, s100, s101
	s_bcnt1_i32_b64 s101, s[16:17]
	s_add_i32 s100, s100, s101
	v_cmp_le_u32_e64 vcc, s15, v8
	v_cmp_le_u32_e64 s[16:17], s15, v6
	s_bcnt1_i32_b64 s101, vcc
	s_add_i32 s100, s100, s101
	s_bcnt1_i32_b64 s101, s[16:17]
	s_add_i32 s100, s100, s101
	v_cmp_le_u32_e64 vcc, s15, v4
	v_cmp_le_u32_e64 s[16:17], s15, v2
	s_bcnt1_i32_b64 s101, vcc
	s_add_i32 s100, s100, s101
	s_bcnt1_i32_b64 s101, s[16:17]
	s_add_i32 s100, s100, s101
	s_cmp_gt_i32 s100, s50
	s_cselect_b32 s32, s15, s32
	s_add_i32 s14, s14, -1
	s_cmp_eq_u32 s14, -1
	s_cbranch_scc0 .LBB0_3414
	v_mov_b32_e32 v40, s32
	v_mov_b32_e32 v41, v103
	v_readfirstlane_b32 s14, v40
	v_cmp_lt_u32 vcc, s14, v32
	v_addc_co_u32 v41, vcc, 0, v41, vcc
	v_cmp_ne_u32_e64 s[16:17], 0, v32
	v_cmp_lt_u32 vcc, s14, v30
	v_addc_co_u32 v41, vcc, 0, v41, vcc
	s_nop 0
	v_cmp_lt_u32 vcc, s14, v28
	v_addc_co_u32 v41, vcc, 0, v41, vcc
	s_nop 0
	v_cmp_lt_u32 vcc, s14, v26
	v_addc_co_u32 v41, vcc, 0, v41, vcc
	s_nop 0
	v_cmp_lt_u32 vcc, s14, v24
	v_addc_co_u32 v41, vcc, 0, v41, vcc
	s_nop 0
	v_cmp_lt_u32 vcc, s14, v22
	v_addc_co_u32 v41, vcc, 0, v41, vcc
	s_nop 0
	v_cmp_lt_u32 vcc, s14, v20
	v_addc_co_u32 v41, vcc, 0, v41, vcc
	s_nop 0
	v_cmp_lt_u32 vcc, s14, v18
	v_addc_co_u32 v41, vcc, 0, v41, vcc
	s_nop 0
	v_cmp_lt_u32 vcc, s14, v16
	v_addc_co_u32 v41, vcc, 0, v41, vcc
	s_nop 0
	v_cmp_lt_u32 vcc, s14, v14
	v_addc_co_u32 v41, vcc, 0, v41, vcc
	s_nop 0
	v_cmp_lt_u32 vcc, s14, v12
	v_addc_co_u32 v41, vcc, 0, v41, vcc
	s_nop 0
	v_cmp_lt_u32 vcc, s14, v10
	v_addc_co_u32 v41, vcc, 0, v41, vcc
	s_nop 0
	v_cmp_lt_u32 vcc, s14, v8
	v_addc_co_u32 v41, vcc, 0, v41, vcc
	s_nop 0
	v_cmp_lt_u32 vcc, s14, v6
	v_addc_co_u32 v41, vcc, 0, v41, vcc
	s_nop 0
	v_cmp_lt_u32 vcc, s14, v4
	v_addc_co_u32 v41, vcc, 0, v41, vcc
	s_nop 0
	v_cmp_lt_u32 vcc, s14, v2
	v_addc_co_u32 v41, vcc, 0, v41, vcc
	ds_bpermute_b32 v42, v35, v41
	v_cmp_eq_u32_e64 s[14:15], v32, v40
	s_and_b64 s[18:19], s[16:17], s[14:15]
	v_cmp_gt_u32_e32 vcc, v32, v40
	v_cndmask_b32_e64 v32, 0, 1, s[18:19]
	s_waitcnt lgkmcnt(0)
	v_add_u32_e32 v41, v42, v41
	ds_bpermute_b32 v42, v36, v41
	v_cmp_ne_u32_e64 s[14:15], 0, v32
	s_waitcnt lgkmcnt(0)
	v_add_u32_e32 v41, v42, v41
	ds_bpermute_b32 v42, v37, v41
	s_waitcnt lgkmcnt(0)
	v_add_u32_e32 v41, v42, v41
	ds_bpermute_b32 v42, v38, v41
	s_waitcnt lgkmcnt(0)
	v_add_u32_e32 v41, v42, v41
	ds_bpermute_b32 v42, v39, v41
	s_waitcnt lgkmcnt(0)
	v_add_u32_e32 v41, v42, v41
	ds_bpermute_b32 v42, v34, v41
	s_and_saveexec_b64 s[16:17], vcc
	s_cbranch_execz .LBB0_3417
	v_and_b32_e32 v43, vcc_lo, v0
	v_and_b32_e32 v32, vcc_hi, v1
	v_bcnt_u32_b32 v43, v43, 0
	v_bcnt_u32_b32 v32, v32, v43
	v_lshlrev_b32_e32 v32, 2, v32
	global_store_dword v32, v33, s[42:43]

; #define LDS_WAIT() asm volatile("s_waitcnt lgkmcnt(0)" ::: "memory")
; template <int NPL>
; DI void topk_row2(const float* sc, int n, int* idx_out, LAS unsigned* cbuf  , int lane_) {
;     ...
;     const int ncand = __builtin_amdgcn_readfirstlane(base);
;     if (ncand > TK_CAP) { topk_row<NPL>(sc, n, idx_out, lane_); return; }
;     LDS_WAIT(); asm volatile("" ::: "memory");
;     unsigned ck[TK_CPL], ci[TK_CPL];
; #pragma unroll
;     for (int c = 0; c < TK_CPL; ++c) { const int q = lane2 + 64 * c; const bool v = q < ncand; ck[c] = v ? cbuf[q] : 0u; ci[c] = v ? cbuf[TK_CAP + q] : 0u; }
;     unsigned Tk = 0u;
; #pragma unroll 1
.LBB0_4318:
	s_cmpk_lt_i32 s16, 0x401
	s_mov_b64 s[14:15], -1
	s_cbranch_scc0 .LBB0_4418
	s_waitcnt lgkmcnt(0)
	v_cmp_gt_i32_e32 vcc, s16, v40
	v_mov_b32_e32 v30, 0
	v_lshl_add_u32 v41, v40, 2, s3
	v_mov_b32_e32 v32, 0
	v_mov_b32_e32 v33, 0
	s_and_saveexec_b64 s[14:15], vcc
	ds_read2st64_b32 v[32:33], v41 offset1:16
	s_or_b64 exec, exec, s[14:15]
	v_add_u32_e32 v2, 64, v40
	v_cmp_gt_i32_e32 vcc, s16, v2
	v_mov_b32_e32 v31, 0
	s_and_saveexec_b64 s[14:15], vcc
	ds_read2st64_b32 v[30:31], v41 offset0:1 offset1:17
	s_or_b64 exec, exec, s[14:15]
	v_add_u32_e32 v2, 0x80, v40
	v_cmp_gt_i32_e32 vcc, s16, v2
	v_mov_b32_e32 v26, 0
	v_mov_b32_e32 v28, 0
	v_mov_b32_e32 v29, 0
	s_and_saveexec_b64 s[14:15], vcc
	ds_read2st64_b32 v[28:29], v41 offset0:2 offset1:18
	s_or_b64 exec, exec, s[14:15]
	v_add_u32_e32 v2, 0xc0, v40
	v_cmp_gt_i32_e32 vcc, s16, v2
	v_mov_b32_e32 v27, 0
	s_and_saveexec_b64 s[14:15], vcc
	ds_read2st64_b32 v[26:27], v41 offset0:3 offset1:19
	s_or_b64 exec, exec, s[14:15]
	v_add_u32_e32 v2, 0x100, v40
	v_cmp_gt_i32_e32 vcc, s16, v2
	v_mov_b32_e32 v22, 0
	v_mov_b32_e32 v24, 0
	v_mov_b32_e32 v25, 0
	s_and_saveexec_b64 s[14:15], vcc
	ds_read2st64_b32 v[24:25], v41 offset0:4 offset1:20
	s_or_b64 exec, exec, s[14:15]
	v_add_u32_e32 v2, 0x140, v40
	v_cmp_gt_i32_e32 vcc, s16, v2
	v_mov_b32_e32 v23, 0
	s_and_saveexec_b64 s[14:15], vcc
	ds_read2st64_b32 v[22:23], v41 offset0:5 offset1:21
	s_or_b64 exec, exec, s[14:15]
	v_add_u32_e32 v2, 0x180, v40
	v_cmp_gt_i32_e32 vcc, s16, v2
	v_mov_b32_e32 v18, 0
	v_mov_b32_e32 v20, 0
	v_mov_b32_e32 v21, 0
	s_and_saveexec_b64 s[14:15], vcc
	ds_read2st64_b32 v[20:21], v41 offset0:6 offset1:22
	s_or_b64 exec, exec, s[14:15]
	v_add_u32_e32 v2, 0x1c0, v40
	v_cmp_gt_i32_e32 vcc, s16, v2
	v_mov_b32_e32 v19, 0
	s_and_saveexec_b64 s[14:15], vcc
	ds_read2st64_b32 v[18:19], v41 offset0:7 offset1:23
	s_or_b64 exec, exec, s[14:15]
	v_add_u32_e32 v2, 0x200, v40
	v_cmp_gt_i32_e32 vcc, s16, v2
	v_mov_b32_e32 v14, 0
	v_mov_b32_e32 v16, 0
	v_mov_b32_e32 v17, 0
	s_and_saveexec_b64 s[14:15], vcc
	ds_read2st64_b32 v[16:17], v41 offset0:8 offset1:24
	s_or_b64 exec, exec, s[14:15]
	v_add_u32_e32 v2, 0x240, v40
	v_cmp_gt_i32_e32 vcc, s16, v2
	v_mov_b32_e32 v15, 0
	s_and_saveexec_b64 s[14:15], vcc
	ds_read2st64_b32 v[14:15], v41 offset0:9 offset1:25
	s_or_b64 exec, exec, s[14:15]
	v_add_u32_e32 v2, 0x280, v40
	v_cmp_gt_i32_e32 vcc, s16, v2
	v_mov_b32_e32 v10, 0
	v_mov_b32_e32 v12, 0
	v_mov_b32_e32 v13, 0
	s_and_saveexec_b64 s[14:15], vcc
	ds_read2st64_b32 v[12:13], v41 offset0:10 offset1:26
	s_or_b64 exec, exec, s[14:15]
	v_add_u32_e32 v2, 0x2c0, v40
	v_cmp_gt_i32_e32 vcc, s16, v2
	v_mov_b32_e32 v11, 0
	s_and_saveexec_b64 s[14:15], vcc
	ds_read2st64_b32 v[10:11], v41 offset0:11 offset1:27
	s_or_b64 exec, exec, s[14:15]
	v_add_u32_e32 v2, 0x300, v40
	v_cmp_gt_i32_e32 vcc, s16, v2
	v_mov_b32_e32 v6, 0
	v_mov_b32_e32 v8, 0
	v_mov_b32_e32 v9, 0
	s_and_saveexec_b64 s[14:15], vcc
	ds_read2st64_b32 v[8:9], v41 offset0:12 offset1:28
	s_or_b64 exec, exec, s[14:15]
	v_add_u32_e32 v2, 0x340, v40
	v_cmp_gt_i32_e32 vcc, s16, v2
	v_mov_b32_e32 v7, 0
	s_and_saveexec_b64 s[14:15], vcc
	ds_read2st64_b32 v[6:7], v41 offset0:13 offset1:29
	s_or_b64 exec, exec, s[14:15]
	v_add_u32_e32 v2, 0x380, v40
	v_cmp_gt_i32_e32 vcc, s16, v2
	v_mov_b32_e32 v2, 0
	v_mov_b32_e32 v4, 0
	v_mov_b32_e32 v5, 0
	s_and_saveexec_b64 s[14:15], vcc
	ds_read2st64_b32 v[4:5], v41 offset0:14 offset1:30
	s_or_b64 exec, exec, s[14:15]
	v_add_u32_e32 v3, 0x3c0, v40
	v_cmp_gt_i32_e32 vcc, s16, v3
	v_mov_b32_e32 v3, 0
	s_and_saveexec_b64 s[14:15], vcc
	ds_read2st64_b32 v[2:3], v41 offset0:15 offset1:31
	s_or_b64 exec, exec, s[14:15]
	v_mov_b32_e32 v40, 0
	s_mov_b32 s14, 31
	s_mov_b32 s32, 0

; #define LDS_WAIT() asm volatile("s_waitcnt lgkmcnt(0)" ::: "memory")
; template <int NPL>
; DI void topk_row2(const float* sc, int n, int* idx_out, LAS unsigned* cbuf  , int lane_) {
;     ...
;     const int ncand = __builtin_amdgcn_readfirstlane(base);
;     if (ncand > TK_CAP) { topk_row<NPL>(sc, n, idx_out, lane_); return; }
;     LDS_WAIT(); asm volatile("" ::: "memory");
;     unsigned ck[TK_CPL], ci[TK_CPL];
; #pragma unroll
;     for (int c = 0; c < TK_CPL; ++c) { const int q = lane2 + 64 * c; const bool v = q < ncand; ck[c] = v ? cbuf[q] : 0u; ci[c] = v ? cbuf[TK_CAP + q] : 0u; }
;     unsigned Tk = 0u;
; #pragma unroll 1
.LBB0_4940:
	s_cmpk_lt_i32 s16, 0x401
	s_mov_b64 s[14:15], -1
	s_cbranch_scc0 .LBB0_5040
	s_waitcnt lgkmcnt(0)
	v_cmp_gt_i32_e32 vcc, s16, v3
	v_mov_b32_e32 v30, 0
	v_lshl_add_u32 v40, v3, 2, s3
	v_mov_b32_e32 v32, 0
	v_mov_b32_e32 v33, 0
	s_and_saveexec_b64 s[14:15], vcc
	ds_read2st64_b32 v[32:33], v40 offset1:16
	s_or_b64 exec, exec, s[14:15]
	v_add_u32_e32 v2, 64, v3
	v_cmp_gt_i32_e32 vcc, s16, v2
	v_mov_b32_e32 v31, 0
	s_and_saveexec_b64 s[14:15], vcc
	ds_read2st64_b32 v[30:31], v40 offset0:1 offset1:17
	s_or_b64 exec, exec, s[14:15]
	v_add_u32_e32 v2, 0x80, v3
	v_cmp_gt_i32_e32 vcc, s16, v2
	v_mov_b32_e32 v26, 0
	v_mov_b32_e32 v28, 0
	v_mov_b32_e32 v29, 0
	s_and_saveexec_b64 s[14:15], vcc
	ds_read2st64_b32 v[28:29], v40 offset0:2 offset1:18
	s_or_b64 exec, exec, s[14:15]
	v_add_u32_e32 v2, 0xc0, v3
	v_cmp_gt_i32_e32 vcc, s16, v2
	v_mov_b32_e32 v27, 0
	s_and_saveexec_b64 s[14:15], vcc
	ds_read2st64_b32 v[26:27], v40 offset0:3 offset1:19
	s_or_b64 exec, exec, s[14:15]
	v_add_u32_e32 v2, 0x100, v3
	v_cmp_gt_i32_e32 vcc, s16, v2
	v_mov_b32_e32 v22, 0
	v_mov_b32_e32 v24, 0
	v_mov_b32_e32 v25, 0
	s_and_saveexec_b64 s[14:15], vcc
	ds_read2st64_b32 v[24:25], v40 offset0:4 offset1:20
	s_or_b64 exec, exec, s[14:15]
	v_add_u32_e32 v2, 0x140, v3
	v_cmp_gt_i32_e32 vcc, s16, v2
	v_mov_b32_e32 v23, 0
	s_and_saveexec_b64 s[14:15], vcc
	ds_read2st64_b32 v[22:23], v40 offset0:5 offset1:21
	s_or_b64 exec, exec, s[14:15]
	v_add_u32_e32 v2, 0x180, v3
	v_cmp_gt_i32_e32 vcc, s16, v2
	v_mov_b32_e32 v18, 0
	v_mov_b32_e32 v20, 0
	v_mov_b32_e32 v21, 0
	s_and_saveexec_b64 s[14:15], vcc
	ds_read2st64_b32 v[20:21], v40 offset0:6 offset1:22
	s_or_b64 exec, exec, s[14:15]
	v_add_u32_e32 v2, 0x1c0, v3
	v_cmp_gt_i32_e32 vcc, s16, v2
	v_mov_b32_e32 v19, 0
	s_and_saveexec_b64 s[14:15], vcc
	ds_read2st64_b32 v[18:19], v40 offset0:7 offset1:23
	s_or_b64 exec, exec, s[14:15]
	v_add_u32_e32 v2, 0x200, v3
	v_cmp_gt_i32_e32 vcc, s16, v2
	v_mov_b32_e32 v14, 0
	v_mov_b32_e32 v16, 0
	v_mov_b32_e32 v17, 0
	s_and_saveexec_b64 s[14:15], vcc
	ds_read2st64_b32 v[16:17], v40 offset0:8 offset1:24
	s_or_b64 exec, exec, s[14:15]
	v_add_u32_e32 v2, 0x240, v3
	v_cmp_gt_i32_e32 vcc, s16, v2
	v_mov_b32_e32 v15, 0
	s_and_saveexec_b64 s[14:15], vcc
	ds_read2st64_b32 v[14:15], v40 offset0:9 offset1:25
	s_or_b64 exec, exec, s[14:15]
	v_add_u32_e32 v2, 0x280, v3
	v_cmp_gt_i32_e32 vcc, s16, v2
	v_mov_b32_e32 v10, 0
	v_mov_b32_e32 v12, 0
	v_mov_b32_e32 v13, 0
	s_and_saveexec_b64 s[14:15], vcc
	ds_read2st64_b32 v[12:13], v40 offset0:10 offset1:26
	s_or_b64 exec, exec, s[14:15]
	v_add_u32_e32 v2, 0x2c0, v3
	v_cmp_gt_i32_e32 vcc, s16, v2
	v_mov_b32_e32 v11, 0
	s_and_saveexec_b64 s[14:15], vcc
	ds_read2st64_b32 v[10:11], v40 offset0:11 offset1:27
	s_or_b64 exec, exec, s[14:15]
	v_add_u32_e32 v2, 0x300, v3
	v_cmp_gt_i32_e32 vcc, s16, v2
	v_mov_b32_e32 v6, 0
	v_mov_b32_e32 v8, 0
	v_mov_b32_e32 v9, 0
	s_and_saveexec_b64 s[14:15], vcc
	ds_read2st64_b32 v[8:9], v40 offset0:12 offset1:28
	s_or_b64 exec, exec, s[14:15]
	v_add_u32_e32 v2, 0x340, v3
	v_cmp_gt_i32_e32 vcc, s16, v2
	v_mov_b32_e32 v7, 0
	s_and_saveexec_b64 s[14:15], vcc
	ds_read2st64_b32 v[6:7], v40 offset0:13 offset1:29
	s_or_b64 exec, exec, s[14:15]
	v_add_u32_e32 v2, 0x380, v3
	v_cmp_gt_i32_e32 vcc, s16, v2
	v_mov_b32_e32 v2, 0
	v_mov_b32_e32 v4, 0
	v_mov_b32_e32 v5, 0
	s_and_saveexec_b64 s[14:15], vcc
	ds_read2st64_b32 v[4:5], v40 offset0:14 offset1:30
	s_or_b64 exec, exec, s[14:15]
	v_add_u32_e32 v3, 0x3c0, v3
	v_cmp_gt_i32_e32 vcc, s16, v3
	v_mov_b32_e32 v3, 0
	s_and_saveexec_b64 s[14:15], vcc
	ds_read2st64_b32 v[2:3], v40 offset0:15 offset1:31
	s_or_b64 exec, exec, s[14:15]
	v_mov_b32_e32 v40, 0
	s_mov_b32 s14, 31
	s_mov_b32 s32, 0
